# retention chunk KV^T: f32 FMA loop replaced by v_mfma_f32_32x32x2_f32 on four waves (same f32 math, fewer LDS reads)
# speedup vs baseline: 1.0055x; 1.0055x over previous
.LBB0_374:
	s_bfe_u32 s6, s8, 0x20005
	v_cvt_f32_ubyte0_e32 v0, s6
	v_sub_f32_e32 v19, 0xc0a00000, v0
	s_ashr_i32 s10, s8, 7
	v_cmp_gt_f32_e32 vcc, s37, v19
	s_and_b64 s[14:15], vcc, exec
	v_mov_b32_e32 v18, v152
	s_cselect_b32 s9, 0xffffffc0, 0
	s_ashr_i32 s11, s10, 31
	s_lshl_b32 s14, s8, 7
	s_lshl_b64 s[10:11], s[10:11], 12
	v_ashrrev_i32_e32 v0, 5, v18
	s_and_b32 s14, s14, 0xf80
	s_or_b32 s10, s10, s14
	s_lshl_b32 s6, s6, 7
	v_ashrrev_i32_e32 v1, 31, v0
	s_waitcnt vmcnt(2)
	v_add_u32_e32 v14, 16, v0
	s_add_u32 s14, s4, s6
	v_lshl_add_u64 v[20:21], s[10:11], 0, v[0:1]
	s_waitcnt vmcnt(1)
	v_ashrrev_i32_e32 v15, 31, v14
	v_and_b32_e32 v44, 31, v18
	s_addc_u32 s15, s5, 0
	v_lshlrev_b64 v[2:3], 11, v[20:21]
	v_lshl_add_u64 v[22:23], s[10:11], 0, v[14:15]
	v_add_u32_e32 v12, 32, v0
	v_lshl_add_u64 v[2:3], s[14:15], 0, v[2:3]
	v_lshlrev_b32_e32 v8, 1, v44
	v_lshlrev_b64 v[4:5], 11, v[22:23]
	v_ashrrev_i32_e32 v13, 31, v12
	s_waitcnt vmcnt(0)
	v_add_u32_e32 v16, 48, v0
	v_lshl_add_u64 v[2:3], v[2:3], 0, v[8:9]
	v_lshl_add_u64 v[4:5], s[14:15], 0, v[4:5]
	v_lshl_add_u64 v[28:29], s[10:11], 0, v[12:13]
	v_ashrrev_i32_e32 v17, 31, v16
	s_barrier
	v_lshl_add_u64 v[4:5], v[4:5], 0, v[8:9]
	global_load_ushort v1, v[2:3], off offset:512
	global_load_ushort v15, v[2:3], off offset:576
	global_load_ushort v45, v[4:5], off offset:512
	global_load_ushort v46, v[4:5], off offset:576
	v_lshlrev_b64 v[2:3], 11, v[28:29]
	v_lshl_add_u64 v[30:31], s[10:11], 0, v[16:17]
	v_lshl_add_u64 v[2:3], s[14:15], 0, v[2:3]
	v_lshlrev_b64 v[4:5], 11, v[30:31]
	v_lshl_add_u64 v[2:3], v[2:3], 0, v[8:9]
	v_lshl_add_u64 v[4:5], s[14:15], 0, v[4:5]
	v_lshl_add_u64 v[4:5], v[4:5], 0, v[8:9]
	global_load_ushort v13, v[2:3], off offset:512
	global_load_ushort v17, v[2:3], off offset:576
	global_load_ushort v47, v[4:5], off offset:512
	global_load_ushort v48, v[4:5], off offset:576
	v_add_u32_e32 v2, 64, v0
	v_ashrrev_i32_e32 v3, 31, v2
	v_lshl_add_u64 v[32:33], s[10:11], 0, v[2:3]
	v_lshlrev_b64 v[4:5], 11, v[32:33]
	v_lshl_add_u64 v[4:5], s[14:15], 0, v[4:5]
	v_lshl_add_u64 v[6:7], v[4:5], 0, v[8:9]
	v_add_u32_e32 v4, 0x50, v0
	v_ashrrev_i32_e32 v5, 31, v4
	v_lshl_add_u64 v[34:35], s[10:11], 0, v[4:5]
	v_lshlrev_b64 v[10:11], 11, v[34:35]
	v_lshl_add_u64 v[10:11], s[14:15], 0, v[10:11]
	v_lshl_add_u64 v[10:11], v[10:11], 0, v[8:9]
	global_load_ushort v3, v[6:7], off offset:512
	global_load_ushort v5, v[6:7], off offset:576
	global_load_ushort v49, v[10:11], off offset:512
	global_load_ushort v50, v[10:11], off offset:576
	v_add_u32_e32 v6, 0x60, v0
	v_ashrrev_i32_e32 v7, 31, v6
	v_lshl_add_u64 v[36:37], s[10:11], 0, v[6:7]
	v_lshlrev_b64 v[10:11], 11, v[36:37]
	v_lshl_add_u64 v[10:11], s[14:15], 0, v[10:11]
	v_lshl_add_u64 v[38:39], v[10:11], 0, v[8:9]
	v_add_u32_e32 v10, 0x70, v0
	v_ashrrev_i32_e32 v11, 31, v10
	v_lshl_add_u64 v[40:41], s[10:11], 0, v[10:11]
	v_lshlrev_b64 v[42:43], 11, v[40:41]
	v_lshl_add_u64 v[42:43], s[14:15], 0, v[42:43]
	global_load_ushort v7, v[38:39], off offset:512
	v_lshl_add_u64 v[42:43], v[42:43], 0, v[8:9]
	global_load_ushort v8, v[38:39], off offset:576
	global_load_ushort v11, v[42:43], off offset:512
	v_cndmask_b32_e32 v27, 0, v24, vcc
	v_add_f32_e32 v19, v19, v27
	v_lshlrev_b64 v[20:21], 7, v[20:21]
	global_load_ushort v27, v[42:43], off offset:576
	v_lshlrev_b32_e32 v42, 2, v44
	v_or_b32_e32 v20, v20, v42
	v_lshl_add_u64 v[38:39], s[20:21], 0, v[20:21]
	v_lshl_add_u64 v[20:21], s[22:23], 0, v[20:21]
	global_load_dword v43, v[20:21], off
	global_load_dword v44, v[38:39], off
	v_lshlrev_b64 v[20:21], 7, v[22:23]
	v_or_b32_e32 v20, v20, v42
	v_lshl_add_u64 v[22:23], s[20:21], 0, v[20:21]
	v_lshl_add_u64 v[20:21], s[22:23], 0, v[20:21]
	global_load_dword v38, v[22:23], off
	global_load_dword v39, v[20:21], off
	v_lshlrev_b64 v[20:21], 7, v[28:29]
	v_or_b32_e32 v20, v20, v42
	v_lshlrev_b64 v[28:29], 7, v[30:31]
	v_lshl_add_u64 v[22:23], s[20:21], 0, v[20:21]
	v_or_b32_e32 v28, v28, v42
	v_lshl_add_u64 v[20:21], s[22:23], 0, v[20:21]
	v_lshl_add_u64 v[30:31], s[20:21], 0, v[28:29]
	v_lshl_add_u64 v[28:29], s[22:23], 0, v[28:29]
	global_load_dword v51, v[22:23], off
	global_load_dword v52, v[20:21], off
	global_load_dword v53, v[30:31], off
	global_load_dword v54, v[28:29], off
	v_exp_f32_e32 v19, v19
	v_lshlrev_b64 v[20:21], 7, v[32:33]
	v_or_b32_e32 v20, v20, v42
	v_lshlrev_b64 v[28:29], 7, v[34:35]
	v_ldexp_f32 v19, v19, s9
	v_sub_f32_e32 v19, 1.0, v19
	v_lshl_add_u64 v[22:23], s[20:21], 0, v[20:21]
	v_lshl_add_u64 v[20:21], s[22:23], 0, v[20:21]
	v_or_b32_e32 v28, v28, v42
	v_cmp_gt_f32_e32 vcc, s42, v19
	v_lshl_add_u64 v[30:31], s[20:21], 0, v[28:29]
	v_lshl_add_u64 v[28:29], s[22:23], 0, v[28:29]
	global_load_dword v32, v[22:23], off
	global_load_dword v33, v[20:21], off
	global_load_dword v34, v[30:31], off
	global_load_dword v35, v[28:29], off
	v_lshlrev_b64 v[20:21], 7, v[36:37]
	s_and_b64 s[14:15], vcc, exec
	v_or_b32_e32 v20, v20, v42
	v_lshlrev_b64 v[28:29], 7, v[40:41]
	s_cselect_b32 s9, 32, 0
	v_lshl_add_u64 v[22:23], s[20:21], 0, v[20:21]
	v_lshl_add_u64 v[20:21], s[22:23], 0, v[20:21]
	v_or_b32_e32 v28, v28, v42
	v_ldexp_f32 v19, v19, s9
	v_lshl_add_u64 v[30:31], s[20:21], 0, v[28:29]
	v_lshl_add_u64 v[28:29], s[22:23], 0, v[28:29]
	global_load_dword v36, v[22:23], off
	global_load_dword v37, v[20:21], off
	global_load_dword v40, v[30:31], off
	global_load_dword v41, v[28:29], off
	v_log_f32_e32 v19, v19
	v_sub_u32_e32 v21, 0x7f, v0
	v_cvt_f32_i32_e32 v21, v21
	v_cndmask_b32_e32 v20, 0, v25, vcc
	v_sub_f32_e32 v19, v19, v20
	s_waitcnt vmcnt(30)
	v_lshlrev_b32_e32 v15, 16, v15
	v_lshlrev_b32_e32 v1, 16, v1
	v_add_u32_e32 v42, 0, v42
	v_lshl_add_u32 v22, v0, 8, v42
	s_waitcnt vmcnt(28)
	v_lshlrev_b32_e32 v46, 16, v46
	v_lshlrev_b32_e32 v45, 16, v45
	v_lshl_add_u32 v14, v14, 8, v42
	s_waitcnt vmcnt(26)
	v_lshlrev_b32_e32 v17, 16, v17
	v_lshlrev_b32_e32 v13, 16, v13
	v_lshl_add_u32 v12, v12, 8, v42
	s_waitcnt vmcnt(24)
	v_lshlrev_b32_e32 v48, 16, v48
	v_lshlrev_b32_e32 v47, 16, v47
	s_waitcnt vmcnt(22)
	v_lshlrev_b32_e32 v5, 16, v5
	v_lshlrev_b32_e32 v3, 16, v3
	v_lshl_add_u32 v2, v2, 8, v42
	s_waitcnt vmcnt(20)
	v_lshlrev_b32_e32 v50, 16, v50
	v_lshlrev_b32_e32 v49, 16, v49
	v_lshl_add_u32 v4, v4, 8, v42
	s_waitcnt vmcnt(19)
	v_lshlrev_b32_e32 v7, 16, v7
	s_waitcnt vmcnt(18)
	v_lshlrev_b32_e32 v55, 16, v8
	v_mul_f32_e32 v8, v19, v21
	v_cmp_gt_f32_e32 vcc, s37, v8
	s_waitcnt vmcnt(17)
	v_lshlrev_b32_e32 v11, 16, v11
	s_waitcnt vmcnt(16)
	v_lshlrev_b32_e32 v27, 16, v27
	v_cndmask_b32_e32 v8, 0, v24, vcc
	v_fmac_f32_e32 v8, v19, v21
	v_exp_f32_e32 v8, v8
	v_sub_u32_e32 v21, 0x6f, v0
	v_cvt_f32_i32_e32 v21, v21
	v_cndmask_b32_e32 v20, 0, v26, vcc
	v_ldexp_f32 v8, v8, v20
	s_waitcnt vmcnt(15)
	v_mul_f32_e32 v20, v43, v15
	s_waitcnt vmcnt(14)
	v_mul_f32_e32 v15, v44, v15
	v_fma_f32 v20, v44, v1, -v20
	v_fmac_f32_e32 v15, v43, v1
	v_mul_f32_e32 v1, v19, v21
	v_mul_f32_e32 v8, 0x3e000000, v8
	v_cmp_gt_f32_e32 vcc, s37, v1
	v_mul_f32_e32 v20, v8, v20
	v_mul_f32_e32 v8, v8, v15
	v_cndmask_b32_e32 v1, 0, v24, vcc
	v_sub_u32_e32 v15, 0x5f, v0
	v_fmac_f32_e32 v1, v19, v21
	v_cvt_f32_i32_e32 v15, v15
	v_exp_f32_e32 v1, v1
	ds_write2_b32 v22, v20, v8 offset1:32
	v_cndmask_b32_e32 v8, 0, v26, vcc
	v_mul_f32_e32 v21, v19, v15
	v_ldexp_f32 v1, v1, v8
	s_waitcnt vmcnt(12)
	v_mul_f32_e32 v8, v39, v46
	v_mul_f32_e32 v20, v38, v46
	v_cmp_gt_f32_e32 vcc, s37, v21
	v_mul_f32_e32 v1, 0x3e000000, v1
	v_fma_f32 v8, v38, v45, -v8
	v_fmac_f32_e32 v20, v39, v45
	v_cndmask_b32_e32 v21, 0, v24, vcc
	v_mul_f32_e32 v8, v1, v8
	v_fmac_f32_e32 v21, v19, v15
	v_mul_f32_e32 v1, v1, v20
	v_exp_f32_e32 v15, v21
	ds_write2_b32 v14, v8, v1 offset1:32
	v_sub_u32_e32 v14, 0x4f, v0
	v_cvt_f32_i32_e32 v14, v14
	v_cndmask_b32_e32 v1, 0, v26, vcc
	v_ldexp_f32 v1, v15, v1
	s_waitcnt vmcnt(10)
	v_mul_f32_e32 v8, v52, v17
	v_mul_f32_e32 v15, v51, v17
	v_fma_f32 v8, v51, v13, -v8
	v_fmac_f32_e32 v15, v52, v13
	v_mul_f32_e32 v13, v19, v14
	v_cmp_gt_f32_e32 vcc, s37, v13
	v_mul_f32_e32 v1, 0x3e000000, v1
	v_mul_f32_e32 v8, v1, v8
	v_cndmask_b32_e32 v13, 0, v24, vcc
	v_fmac_f32_e32 v13, v19, v14
	v_exp_f32_e32 v13, v13
	v_mul_f32_e32 v1, v1, v15
	v_sub_u32_e32 v14, 63, v0
	ds_write2_b32 v12, v8, v1 offset1:32
	v_cndmask_b32_e32 v1, 0, v26, vcc
	v_cvt_f32_i32_e32 v14, v14
	v_ldexp_f32 v1, v13, v1
	s_waitcnt vmcnt(8)
	v_mul_f32_e32 v8, v54, v48
	v_mul_f32_e32 v13, v53, v48
	v_mul_f32_e32 v1, 0x3e000000, v1
	v_fma_f32 v8, v53, v47, -v8
	v_fmac_f32_e32 v13, v54, v47
	v_mul_f32_e32 v8, v1, v8
	v_lshl_add_u32 v12, v16, 8, v42
	v_mul_f32_e32 v1, v1, v13
	ds_write2_b32 v12, v8, v1 offset1:32
	v_mul_f32_e32 v1, v19, v14
	v_cmp_gt_f32_e32 vcc, s37, v1
	v_lshlrev_b32_e32 v8, 3, v18
	v_and_b32_e32 v12, 56, v8
	v_cndmask_b32_e32 v1, 0, v24, vcc
	v_fmac_f32_e32 v1, v19, v14
	v_ashrrev_i32_e32 v14, 3, v18
	v_ashrrev_i32_e32 v15, 31, v14
	v_lshl_add_u64 v[16:17], s[10:11], 0, v[14:15]
	v_lshlrev_b64 v[16:17], 11, v[16:17]
	v_lshl_add_u64 v[16:17], s[4:5], 0, v[16:17]
	v_lshl_add_u64 v[16:17], v[16:17], 0, s[6:7]
	v_lshlrev_b32_e32 v8, 1, v12
	v_lshl_add_u64 v[16:17], v[16:17], 0, v[8:9]
	v_add_u32_e32 v13, 0x200, v18
	global_load_dwordx4 v[20:23], v[16:17], off offset:1024
	v_ashrrev_i32_e32 v16, 3, v13
	v_ashrrev_i32_e32 v17, 31, v16
	v_lshl_add_u64 v[16:17], s[10:11], 0, v[16:17]
	v_lshlrev_b64 v[16:17], 11, v[16:17]
	v_lshl_add_u64 v[16:17], s[4:5], 0, v[16:17]
	v_lshl_add_u64 v[16:17], v[16:17], 0, s[6:7]
	v_lshl_add_u64 v[16:17], v[16:17], 0, v[8:9]
	global_load_dwordx4 v[28:31], v[16:17], off offset:1024
	v_exp_f32_e32 v1, v1
	v_sub_u32_e32 v13, 47, v0
	v_cvt_f32_i32_e32 v13, v13
	v_cndmask_b32_e32 v8, 0, v26, vcc
	v_ldexp_f32 v1, v1, v8
	s_waitcnt vmcnt(8)
	v_mul_f32_e32 v8, v33, v5
	v_mul_f32_e32 v5, v32, v5
	v_fma_f32 v8, v32, v3, -v8
	v_fmac_f32_e32 v5, v33, v3
	v_mul_f32_e32 v3, v19, v13
	v_cmp_gt_f32_e32 vcc, s37, v3
	v_mul_f32_e32 v1, 0x3e000000, v1
	v_mul_f32_e32 v8, v1, v8
	v_cndmask_b32_e32 v3, 0, v24, vcc
	v_fmac_f32_e32 v3, v19, v13
	v_exp_f32_e32 v3, v3
	v_mul_f32_e32 v1, v1, v5
	ds_write2_b32 v2, v8, v1 offset1:32
	v_cndmask_b32_e32 v1, 0, v26, vcc
	v_ldexp_f32 v1, v3, v1
	v_sub_u32_e32 v3, 31, v0
	v_cvt_f32_i32_e32 v3, v3
	v_sub_u32_e32 v0, 15, v0
	v_cvt_f32_i32_e32 v0, v0
	s_waitcnt vmcnt(6)
	v_mul_f32_e32 v2, v35, v50
	v_mul_f32_e32 v8, v19, v3
	v_cmp_gt_f32_e32 vcc, s37, v8
	v_mul_f32_e32 v5, v34, v50
	v_mul_f32_e32 v1, 0x3e000000, v1
	v_cndmask_b32_e32 v8, 0, v24, vcc
	v_fma_f32 v2, v34, v49, -v2
	v_fmac_f32_e32 v5, v35, v49
	v_fmac_f32_e32 v8, v19, v3
	v_mul_f32_e32 v2, v1, v2
	v_exp_f32_e32 v3, v8
	v_mul_f32_e32 v1, v1, v5
	v_mul_f32_e32 v5, v19, v0
	ds_write2_b32 v4, v2, v1 offset1:32
	v_cndmask_b32_e32 v1, 0, v26, vcc
	v_cmp_gt_f32_e32 vcc, s37, v5
	v_ldexp_f32 v1, v3, v1
	s_waitcnt vmcnt(4)
	v_mul_f32_e32 v2, v37, v55
	v_cndmask_b32_e32 v5, 0, v24, vcc
	v_fmac_f32_e32 v5, v19, v0
	v_mul_f32_e32 v4, v36, v55
	v_exp_f32_e32 v0, v5
	v_mul_f32_e32 v1, 0x3e000000, v1
	v_fma_f32 v2, v36, v7, -v2
	v_fmac_f32_e32 v4, v37, v7
	v_mul_f32_e32 v2, v1, v2
	v_lshl_add_u32 v3, v6, 8, v42
	v_mul_f32_e32 v1, v1, v4
	ds_write2_b32 v3, v2, v1 offset1:32
	v_cndmask_b32_e32 v1, 0, v26, vcc
	v_ldexp_f32 v0, v0, v1
	s_waitcnt vmcnt(2)
	v_mul_f32_e32 v1, v41, v27
	v_mul_f32_e32 v3, v40, v27
	v_mul_f32_e32 v0, 0x3e000000, v0
	v_fma_f32 v1, v40, v11, -v1
	v_fmac_f32_e32 v3, v41, v11
	v_mul_f32_e32 v1, v0, v1
	v_lshl_add_u32 v2, v10, 8, v42
	v_mul_f32_e32 v0, v0, v3
	ds_write2_b32 v2, v1, v0 offset1:32
	v_lshlrev_b32_e32 v0, 5, v18
	v_lshl_add_u32 v8, v12, 2, 0
	v_and_b32_e32 v0, 0xffffff00, v0
	v_add_u32_e32 v4, v8, v0
	v_lshl_add_u32 v13, v14, 2, s43
	s_mov_b32 s6, 0
	v_mov_b32_e32 v16, 0
	s_waitcnt vmcnt(1)
	v_lshlrev_b32_e32 v0, 16, v20
	v_and_b32_e32 v1, 0xffff0000, v20
	v_lshlrev_b32_e32 v2, 16, v21
	v_and_b32_e32 v3, 0xffff0000, v21
	ds_write_b128 v4, v[0:3] offset:32768
	v_lshlrev_b32_e32 v0, 16, v22
	v_and_b32_e32 v1, 0xffff0000, v22
	v_lshlrev_b32_e32 v2, 16, v23
	v_and_b32_e32 v3, 0xffff0000, v23
	ds_write_b128 v4, v[0:3] offset:32784
	s_waitcnt vmcnt(0)
	v_lshlrev_b32_e32 v0, 16, v28
	v_and_b32_e32 v1, 0xffff0000, v28
	v_lshlrev_b32_e32 v2, 16, v29
	v_and_b32_e32 v3, 0xffff0000, v29
	ds_write_b128 v4, v[0:3] offset:49152
	v_lshlrev_b32_e32 v0, 16, v30
	v_and_b32_e32 v1, 0xffff0000, v30
	v_lshlrev_b32_e32 v2, 16, v31
	v_and_b32_e32 v3, 0xffff0000, v31
	ds_write_b128 v4, v[0:3] offset:49168
	v_mov_b32_e32 v17, v9
	v_mov_b32_e32 v10, 0
	v_mov_b32_e32 v11, v9
	v_mov_b32_e32 v0, 0
	v_mov_b32_e32 v1, v9
	v_mov_b32_e32 v2, 0
	v_mov_b32_e32 v3, v9
	s_waitcnt lgkmcnt(0)
	s_barrier
	v_cmp_gt_u32_e32 vcc, 0x100, v152
	s_cbranch_vccz .Lrkv_skip_0
	v_and_b32_e32 v86, 31, v152
	v_lshrrev_b32_e32 v87, 5, v152
	v_and_b32_e32 v88, 1, v87
	v_lshlrev_b32_e32 v88, 8, v88
	v_lshl_add_u32 v88, v86, 2, v88
	v_lshrrev_b32_e32 v87, 6, v152
	v_and_b32_e32 v89, 1, v87
	v_lshrrev_b32_e32 v87, 1, v87
	v_lshl_add_u32 v86, v89, 7, v88
	v_add_u32_e32 v86, 0x8000, v86
	v_lshl_add_u32 v87, v87, 7, v88
	ds_read2st64_b32 v[48:49], v86 offset0:0 offset1:2
	ds_read2st64_b32 v[64:65], v87 offset0:0 offset1:2
	ds_read2st64_b32 v[50:51], v86 offset0:4 offset1:6
	ds_read2st64_b32 v[66:67], v87 offset0:4 offset1:6
	ds_read2st64_b32 v[52:53], v86 offset0:8 offset1:10
	ds_read2st64_b32 v[68:69], v87 offset0:8 offset1:10
	ds_read2st64_b32 v[54:55], v86 offset0:12 offset1:14
	ds_read2st64_b32 v[70:71], v87 offset0:12 offset1:14
	ds_read2st64_b32 v[56:57], v86 offset0:16 offset1:18
	ds_read2st64_b32 v[72:73], v87 offset0:16 offset1:18
	ds_read2st64_b32 v[58:59], v86 offset0:20 offset1:22
	ds_read2st64_b32 v[74:75], v87 offset0:20 offset1:22
	ds_read2st64_b32 v[60:61], v86 offset0:24 offset1:26
	ds_read2st64_b32 v[76:77], v87 offset0:24 offset1:26
	ds_read2st64_b32 v[62:63], v86 offset0:28 offset1:30
	ds_read2st64_b32 v[78:79], v87 offset0:28 offset1:30
	s_waitcnt lgkmcnt(0)
	ds_read2st64_b32 v[0:1], v86 offset0:32 offset1:34
	ds_read2st64_b32 v[18:19], v87 offset0:32 offset1:34
	ds_read2st64_b32 v[2:3], v86 offset0:36 offset1:38
	ds_read2st64_b32 v[20:21], v87 offset0:36 offset1:38
	ds_read2st64_b32 v[4:5], v86 offset0:40 offset1:42
	ds_read2st64_b32 v[22:23], v87 offset0:40 offset1:42
	ds_read2st64_b32 v[6:7], v86 offset0:44 offset1:46
	ds_read2st64_b32 v[28:29], v87 offset0:44 offset1:46
	ds_read2st64_b32 v[10:11], v86 offset0:48 offset1:50
	ds_read2st64_b32 v[30:31], v87 offset0:48 offset1:50
	ds_read2st64_b32 v[12:13], v86 offset0:52 offset1:54
	ds_read2st64_b32 v[80:81], v87 offset0:52 offset1:54
	ds_read2st64_b32 v[14:15], v86 offset0:56 offset1:58
	ds_read2st64_b32 v[82:83], v87 offset0:56 offset1:58
	ds_read2st64_b32 v[16:17], v86 offset0:60 offset1:62
	ds_read2st64_b32 v[84:85], v87 offset0:60 offset1:62
	v_mfma_f32_32x32x2_f32 v[32:47], v48, v64, 0
	v_mfma_f32_32x32x2_f32 v[32:47], v49, v65, v[32:47]
	v_mfma_f32_32x32x2_f32 v[32:47], v50, v66, v[32:47]
	v_mfma_f32_32x32x2_f32 v[32:47], v51, v67, v[32:47]
	v_mfma_f32_32x32x2_f32 v[32:47], v52, v68, v[32:47]
	v_mfma_f32_32x32x2_f32 v[32:47], v53, v69, v[32:47]
	v_mfma_f32_32x32x2_f32 v[32:47], v54, v70, v[32:47]
	v_mfma_f32_32x32x2_f32 v[32:47], v55, v71, v[32:47]
	v_mfma_f32_32x32x2_f32 v[32:47], v56, v72, v[32:47]
	v_mfma_f32_32x32x2_f32 v[32:47], v57, v73, v[32:47]
	v_mfma_f32_32x32x2_f32 v[32:47], v58, v74, v[32:47]
	v_mfma_f32_32x32x2_f32 v[32:47], v59, v75, v[32:47]
	v_mfma_f32_32x32x2_f32 v[32:47], v60, v76, v[32:47]
	v_mfma_f32_32x32x2_f32 v[32:47], v61, v77, v[32:47]
	v_mfma_f32_32x32x2_f32 v[32:47], v62, v78, v[32:47]
	v_mfma_f32_32x32x2_f32 v[32:47], v63, v79, v[32:47]
	s_waitcnt lgkmcnt(0)
	v_mfma_f32_32x32x2_f32 v[32:47], v0, v18, v[32:47]
	ds_read2st64_b32 v[48:49], v86 offset0:64 offset1:66
	ds_read2st64_b32 v[64:65], v87 offset0:64 offset1:66
	ds_read2st64_b32 v[50:51], v86 offset0:68 offset1:70
	ds_read2st64_b32 v[66:67], v87 offset0:68 offset1:70
	ds_read2st64_b32 v[52:53], v86 offset0:72 offset1:74
	ds_read2st64_b32 v[68:69], v87 offset0:72 offset1:74
	ds_read2st64_b32 v[54:55], v86 offset0:76 offset1:78
	ds_read2st64_b32 v[70:71], v87 offset0:76 offset1:78
	ds_read2st64_b32 v[56:57], v86 offset0:80 offset1:82
	ds_read2st64_b32 v[72:73], v87 offset0:80 offset1:82
	ds_read2st64_b32 v[58:59], v86 offset0:84 offset1:86
	ds_read2st64_b32 v[74:75], v87 offset0:84 offset1:86
	ds_read2st64_b32 v[60:61], v86 offset0:88 offset1:90
	ds_read2st64_b32 v[76:77], v87 offset0:88 offset1:90
	ds_read2st64_b32 v[62:63], v86 offset0:92 offset1:94
	ds_read2st64_b32 v[78:79], v87 offset0:92 offset1:94
	v_mfma_f32_32x32x2_f32 v[32:47], v1, v19, v[32:47]
	v_mfma_f32_32x32x2_f32 v[32:47], v2, v20, v[32:47]
	v_mfma_f32_32x32x2_f32 v[32:47], v3, v21, v[32:47]
	v_mfma_f32_32x32x2_f32 v[32:47], v4, v22, v[32:47]
	v_mfma_f32_32x32x2_f32 v[32:47], v5, v23, v[32:47]
	v_mfma_f32_32x32x2_f32 v[32:47], v6, v28, v[32:47]
	v_mfma_f32_32x32x2_f32 v[32:47], v7, v29, v[32:47]
	v_mfma_f32_32x32x2_f32 v[32:47], v10, v30, v[32:47]
	v_mfma_f32_32x32x2_f32 v[32:47], v11, v31, v[32:47]
	v_mfma_f32_32x32x2_f32 v[32:47], v12, v80, v[32:47]
	v_mfma_f32_32x32x2_f32 v[32:47], v13, v81, v[32:47]
	v_mfma_f32_32x32x2_f32 v[32:47], v14, v82, v[32:47]
	v_mfma_f32_32x32x2_f32 v[32:47], v15, v83, v[32:47]
	v_mfma_f32_32x32x2_f32 v[32:47], v16, v84, v[32:47]
	v_mfma_f32_32x32x2_f32 v[32:47], v17, v85, v[32:47]
	s_waitcnt lgkmcnt(0)
	v_mfma_f32_32x32x2_f32 v[32:47], v48, v64, v[32:47]
	ds_read2st64_b32 v[0:1], v86 offset0:96 offset1:98
	ds_read2st64_b32 v[18:19], v87 offset0:96 offset1:98
	ds_read2st64_b32 v[2:3], v86 offset0:100 offset1:102
	ds_read2st64_b32 v[20:21], v87 offset0:100 offset1:102
	ds_read2st64_b32 v[4:5], v86 offset0:104 offset1:106
	ds_read2st64_b32 v[22:23], v87 offset0:104 offset1:106
	ds_read2st64_b32 v[6:7], v86 offset0:108 offset1:110
	ds_read2st64_b32 v[28:29], v87 offset0:108 offset1:110
	ds_read2st64_b32 v[10:11], v86 offset0:112 offset1:114
	ds_read2st64_b32 v[30:31], v87 offset0:112 offset1:114
	ds_read2st64_b32 v[12:13], v86 offset0:116 offset1:118
	ds_read2st64_b32 v[80:81], v87 offset0:116 offset1:118
	ds_read2st64_b32 v[14:15], v86 offset0:120 offset1:122
	ds_read2st64_b32 v[82:83], v87 offset0:120 offset1:122
	ds_read2st64_b32 v[16:17], v86 offset0:124 offset1:126
	ds_read2st64_b32 v[84:85], v87 offset0:124 offset1:126
	v_mfma_f32_32x32x2_f32 v[32:47], v49, v65, v[32:47]
	v_mfma_f32_32x32x2_f32 v[32:47], v50, v66, v[32:47]
	v_mfma_f32_32x32x2_f32 v[32:47], v51, v67, v[32:47]
	v_mfma_f32_32x32x2_f32 v[32:47], v52, v68, v[32:47]
	v_mfma_f32_32x32x2_f32 v[32:47], v53, v69, v[32:47]
	v_mfma_f32_32x32x2_f32 v[32:47], v54, v70, v[32:47]
	v_mfma_f32_32x32x2_f32 v[32:47], v55, v71, v[32:47]
	v_mfma_f32_32x32x2_f32 v[32:47], v56, v72, v[32:47]
	v_mfma_f32_32x32x2_f32 v[32:47], v57, v73, v[32:47]
	v_mfma_f32_32x32x2_f32 v[32:47], v58, v74, v[32:47]
	v_mfma_f32_32x32x2_f32 v[32:47], v59, v75, v[32:47]
	v_mfma_f32_32x32x2_f32 v[32:47], v60, v76, v[32:47]
	v_mfma_f32_32x32x2_f32 v[32:47], v61, v77, v[32:47]
	v_mfma_f32_32x32x2_f32 v[32:47], v62, v78, v[32:47]
	v_mfma_f32_32x32x2_f32 v[32:47], v63, v79, v[32:47]
	s_waitcnt lgkmcnt(0)
	v_mfma_f32_32x32x2_f32 v[32:47], v0, v18, v[32:47]
	v_mfma_f32_32x32x2_f32 v[32:47], v1, v19, v[32:47]
	v_mfma_f32_32x32x2_f32 v[32:47], v2, v20, v[32:47]
	v_mfma_f32_32x32x2_f32 v[32:47], v3, v21, v[32:47]
	v_mfma_f32_32x32x2_f32 v[32:47], v4, v22, v[32:47]
	v_mfma_f32_32x32x2_f32 v[32:47], v5, v23, v[32:47]
	v_mfma_f32_32x32x2_f32 v[32:47], v6, v28, v[32:47]
	v_mfma_f32_32x32x2_f32 v[32:47], v7, v29, v[32:47]
	v_mfma_f32_32x32x2_f32 v[32:47], v10, v30, v[32:47]
	v_mfma_f32_32x32x2_f32 v[32:47], v11, v31, v[32:47]
	v_mfma_f32_32x32x2_f32 v[32:47], v12, v80, v[32:47]
	v_mfma_f32_32x32x2_f32 v[32:47], v13, v81, v[32:47]
	v_mfma_f32_32x32x2_f32 v[32:47], v14, v82, v[32:47]
	v_mfma_f32_32x32x2_f32 v[32:47], v15, v83, v[32:47]
	v_mfma_f32_32x32x2_f32 v[32:47], v16, v84, v[32:47]
	v_mfma_f32_32x32x2_f32 v[32:47], v17, v85, v[32:47]
	s_ashr_i32 s9, s8, 31
	s_lshl_b64 s[10:11], s[8:9], 14
	s_add_u32 s10, s35, s10
	s_addc_u32 s11, s36, s11
	v_and_b32_e32 v86, 31, v152
	v_lshrrev_b32_e32 v87, 5, v152
	v_and_b32_e32 v88, 1, v87
	v_lshlrev_b32_e32 v88, 10, v88
	v_lshl_add_u32 v88, v86, 2, v88
	v_lshrrev_b32_e32 v87, 6, v152
	v_and_b32_e32 v86, 1, v87
	v_lshrrev_b32_e32 v87, 1, v87
	v_lshl_add_u32 v88, v86, 13, v88
	v_lshl_add_u32 v88, v87, 7, v88
	v_mov_b32_e32 v89, 0
	v_lshl_add_u64 v[88:89], v[88:89], 0, s[10:11]
	s_movk_i32 s10, 0x1000
	s_mov_b32 s11, 0
	v_lshl_add_u64 v[86:87], v[88:89], 0, s[10:11]
	s_nop 7
	s_nop 7
	global_store_dword v[88:89], v32, off
	global_store_dword v[88:89], v33, off offset:256
	global_store_dword v[88:89], v34, off offset:512
	global_store_dword v[88:89], v35, off offset:768
	global_store_dword v[88:89], v36, off offset:2048
	global_store_dword v[88:89], v37, off offset:2304
	global_store_dword v[88:89], v38, off offset:2560
	global_store_dword v[88:89], v39, off offset:2816
	global_store_dword v[86:87], v40, off
	global_store_dword v[86:87], v41, off offset:256
	global_store_dword v[86:87], v42, off offset:512
	global_store_dword v[86:87], v43, off offset:768
	global_store_dword v[86:87], v44, off offset:2048
	global_store_dword v[86:87], v45, off offset:2304
	global_store_dword v[86:87], v46, off offset:2560
	global_store_dword v[86:87], v47, off offset:2816
.Lrkv_skip_0:
	s_add_i32 s8, s8, s73
	s_cmpk_gt_i32 s8, 0x1ff
	s_cbranch_scc0 .LBB0_374
